# combo12 + lds_base + permlane reductions + 64-byte aligned K-loop headers (combined)
# speedup vs baseline: 1.0043x; 1.0017x over previous
; template <class Epi, class Sched, bool ALIGN_EPI = false, bool SP2 = false, bool ACHUNK = false>
; __device__ __forceinline__ void gemm_phase(PG8_LAS unsigned char* lds, const Gemm g, const Sched& S, const Epi& E) {
;     ...
;         const bool has_next = S.next(ui + 1, nxt);
;         const char* nA = has_next ? (const char*)g.A + (size_t)nxt.pm * tstepA : cA; const char* nB = has_next ? (const char*)g.Bt + (size_t)nxt.pn * tstepB : cB;
;         for (int t = 0; t < nt; t += 2) {
;             const bool last = (t == nt - 2);
;             if constexpr (Epi::HAS_MID) { if (t == Epi::MID_T) E.mid(acc, cur, wr, wc, fr, fq, ShflDev{}); }
;             const char* a1 = cA + (size_t)(t + 1) * kstep;
;             const char* a2 = last ? nA : cA + (size_t)(t + 2) * kstep; const char* b2 = last ? nB : cB + (size_t)(t + 2) * kstep;
.LBB0_51:
	s_add_u32 s20, s20, 0x80
	s_addc_u32 s21, s21, 0
	s_add_u32 s44, s18, 0x100
	s_addc_u32 s45, s19, 0
	s_mov_b32 s18, 0
	v_add_u32_e32 v192, 0x10000, v147
	.p2align	6

; #define PG8_STAGE(bufoff, gbase, voff) do { _Pragma("unroll") for (int _i = 0; _i < 2; ++_i) \
;         __builtin_amdgcn_global_load_lds((const unsigned*)((const char*)(gbase) + (voff)[_i]), (PG8_LAS unsigned*)(lds + (bufoff) + ldsw + _i * 8192), 16, 0, 0); } while (0)
; #define PG8_LDA(dst, b, h) do { _Pragma("unroll") for (int m = 0; m < 4; ++m) _Pragma("unroll") for (int k = 0; k < 2; ++k) dst[m][k] = *(const PG8_LAS bf16x8*)(lds + PG8_SA(b, h) + aoff + m * 2048 + k * 1024); } while (0)
; #define PG8_LDB(dst, b, h) do { _Pragma("unroll") for (int n = 0; n < 2; ++n) _Pragma("unroll") for (int k = 0; k < 2; ++k) dst[n][k] = *(const PG8_LAS bf16x8*)(lds + PG8_SB(b, h) + boff + n * 2048 + k * 1024); } while (0)
; #define PG8_WAIT_V(n) asm volatile("s_waitcnt vmcnt(" #n ")" ::: "memory")
; #define PG8_WAIT_L(n) asm volatile("s_waitcnt lgkmcnt(" #n ")" ::: "memory")
; template <class Epi, class Sched, bool ALIGN_EPI = false, bool SP2 = false, bool ACHUNK = false>
; __device__ __forceinline__ void gemm_phase(PG8_LAS unsigned char* lds, const Gemm g, const Sched& S, const Epi& E) {
;     ...
;         const bool has_next = S.next(ui + 1, nxt);
;         const char* nA = has_next ? (const char*)g.A + (size_t)nxt.pm * tstepA : cA; const char* nB = has_next ? (const char*)g.Bt + (size_t)nxt.pn * tstepB : cB;
;         for (int t = 0; t < nt; t += 2) {
;             const bool last = (t == nt - 2);
;             if constexpr (Epi::HAS_MID) { if (t == Epi::MID_T) E.mid(acc, cur, wr, wc, fr, fq, ShflDev{}); }
;             const char* a1 = cA + (size_t)(t + 1) * kstep;
;             const char* a2 = last ? nA : cA + (size_t)(t + 2) * kstep; const char* b2 = last ? nB : cB + (size_t)(t + 2) * kstep;
;             const char* a3 = a2 + kstep; const char* b3 = b2 + kstep;
;             if (last && has_next) S.a_ready(nxt);
;             if constexpr (SP2) {
;             PG8_LDB(B0, 0, 0); PG8_LDB(B1, 0, 1); PG8_SCHED; PG8_LDA(At, 0, 0); PG8_STAGE(PG8_SA(1, 1), a1 + hstepA, voffA);
;             PG8_WAIT_V(8); PG8_WAIT_L(0); PG8_BAR; PG8_MMA(0, 0, At, B0); PG8_MMA(0, 1, At, B1); PG8_BAR; PG8_SCHED;
;             PG8_LDA(At, 0, 1); PG8_STAGE(PG8_SB(0, 0), b2, voffB); PG8_STAGE(PG8_SB(0, 1), b2 + hstepB, voffB); PG8_STAGE(PG8_SA(0, 0), a2, voffA);
;             PG8_WAIT_V(8); PG8_WAIT_L(0); PG8_BAR; PG8_MMA(1, 0, At, B0); PG8_MMA(1, 1, At, B1); PG8_BAR; PG8_SCHED;
.LBB0_106:
	s_andn2_b64 vcc, exec, s[44:45]
	s_nop 0
	s_cbranch_vccnz .LBB0_110
	s_add_u32 s8, s4, 0x100
	s_addc_u32 s9, s5, 0
	s_add_u32 s0, s6, 0x80
	s_addc_u32 s1, s7, 0
	s_mov_b32 s4, 0
	v_add_u32_e32 v192, 0x10000, v224
	s_add_i32 s6, s4, 2
	s_add_u32 s7, s0, 0x80
	s_addc_u32 s5, s1, 0
	s_add_i32 s77, 0, 0x10000
	s_cmp_eq_u32 s54, s4
	s_cselect_b32 s5, s49, s5
	s_cselect_b32 s4, s48, s7
	s_cselect_b32 s79, s51, s9
	s_cselect_b32 s78, s50, s8
	s_add_i32 s7, 0, 0x14000
	s_waitcnt lgkmcnt(0)
	ds_read_b128 v[36:39], v192
	ds_read_b128 v[40:43], v192 offset:1024
	ds_read_b128 v[44:47], v192 offset:2048
	ds_read_b128 v[48:51], v192 offset:3072
	ds_read_b128 v[52:55], v192 offset:16384
	ds_read_b128 v[56:59], v192 offset:17408
	ds_read_b128 v[60:63], v192 offset:18432
	ds_read_b128 v[64:67], v192 offset:19456
	s_add_u32 s98, s0, s28
	s_addc_u32 s99, s1, s29
	s_add_i32 m0, s25, 0xc000
	ds_read_b128 v[164:167], v238
	ds_read_b128 v[168:171], v238 offset:1024
	ds_read_b128 v[184:187], v238 offset:2048
	ds_read_b128 v[188:191], v238 offset:3072
	ds_read_b128 v[198:201], v238 offset:4096
	ds_read_b128 v[202:205], v238 offset:5120
	ds_read_b128 v[206:209], v238 offset:6144
	ds_read_b128 v[210:213], v238 offset:7168
	global_load_lds_dwordx4 v172, s[98:99]
	s_add_i32 m0, s25, 0xe000
	s_nop 0
	global_load_lds_dwordx4 v176, s[98:99]
	s_waitcnt vmcnt(8)
	s_waitcnt lgkmcnt(0)
	s_barrier
	s_setprio 1
	v_mfma_f32_16x16x32_bf16 v[148:151], v[36:39], v[164:167], 0
	v_mfma_f32_16x16x32_bf16 v[152:155], v[44:47], v[164:167], 0
	v_mfma_f32_16x16x32_bf16 v[132:135], v[36:39], v[184:187], 0
	v_mfma_f32_16x16x32_bf16 v[140:143], v[44:47], v[184:187], 0
	v_mfma_f32_16x16x32_bf16 v[136:139], v[36:39], v[198:201], 0
	v_mfma_f32_16x16x32_bf16 v[144:147], v[44:47], v[198:201], 0
	v_mfma_f32_16x16x32_bf16 v[160:163], v[36:39], v[206:209], 0
	v_mfma_f32_16x16x32_bf16 v[156:159], v[44:47], v[206:209], 0
	v_mfma_f32_16x16x32_bf16 v[148:151], v[40:43], v[168:171], v[148:151]
	v_mfma_f32_16x16x32_bf16 v[152:155], v[48:51], v[168:171], v[152:155]
	v_mfma_f32_16x16x32_bf16 v[132:135], v[40:43], v[188:191], v[132:135]
	v_mfma_f32_16x16x32_bf16 v[140:143], v[48:51], v[188:191], v[140:143]
	v_mfma_f32_16x16x32_bf16 v[136:139], v[40:43], v[202:205], v[136:139]
	v_mfma_f32_16x16x32_bf16 v[144:147], v[48:51], v[202:205], v[144:147]
	v_mfma_f32_16x16x32_bf16 v[160:163], v[40:43], v[210:213], v[160:163]
	v_mfma_f32_16x16x32_bf16 v[156:159], v[48:51], v[210:213], v[156:159]
	s_setprio 0
	s_setprio 1
	v_mfma_f32_16x16x32_bf16 v[124:127], v[52:55], v[164:167], 0
	v_mfma_f32_16x16x32_bf16 v[128:131], v[60:63], v[164:167], 0
	v_mfma_f32_16x16x32_bf16 v[116:119], v[52:55], v[184:187], 0
	v_mfma_f32_16x16x32_bf16 v[120:123], v[60:63], v[184:187], 0
	v_mfma_f32_16x16x32_bf16 v[112:115], v[52:55], v[198:201], 0
	v_mfma_f32_16x16x32_bf16 v[108:111], v[60:63], v[198:201], 0
	v_mfma_f32_16x16x32_bf16 v[104:107], v[52:55], v[206:209], 0
	v_mfma_f32_16x16x32_bf16 v[100:103], v[60:63], v[206:209], 0
	v_mfma_f32_16x16x32_bf16 v[124:127], v[56:59], v[168:171], v[124:127]
	v_mfma_f32_16x16x32_bf16 v[128:131], v[64:67], v[168:171], v[128:131]
	v_mfma_f32_16x16x32_bf16 v[116:119], v[56:59], v[188:191], v[116:119]
	v_mfma_f32_16x16x32_bf16 v[120:123], v[64:67], v[188:191], v[120:123]
	v_mfma_f32_16x16x32_bf16 v[112:115], v[56:59], v[202:205], v[112:115]
	v_mfma_f32_16x16x32_bf16 v[108:111], v[64:67], v[202:205], v[108:111]
	v_mfma_f32_16x16x32_bf16 v[104:107], v[56:59], v[210:213], v[104:107]
	v_mfma_f32_16x16x32_bf16 v[100:103], v[64:67], v[210:213], v[100:103]
	s_setprio 0
	s_barrier
	s_add_i32 s77, s77, s17
	s_add_u32 s98, s78, s18
	s_addc_u32 s99, s79, s19
	s_mov_b32 m0, s77
	ds_read_b128 v[164:167], v238 offset:16384
	ds_read_b128 v[168:171], v238 offset:17408
	ds_read_b128 v[184:187], v238 offset:18432
	ds_read_b128 v[188:191], v238 offset:19456
	ds_read_b128 v[198:201], v238 offset:20480
	ds_read_b128 v[202:205], v238 offset:21504
	ds_read_b128 v[206:209], v238 offset:22528
	ds_read_b128 v[210:213], v238 offset:23552
	global_load_lds_dwordx4 v174, s[78:79]
	s_add_i32 m0, s77, 0x2000
	s_add_i32 s7, s7, s17
	global_load_lds_dwordx4 v178, s[78:79]
	s_mov_b32 m0, s7
	s_nop 0
	global_load_lds_dwordx4 v174, s[98:99]
	s_add_i32 m0, s7, 0x2000
	s_nop 0
	global_load_lds_dwordx4 v178, s[98:99]
	s_mov_b32 m0, s25
	s_nop 0
	global_load_lds_dwordx4 v172, s[4:5]
	s_mov_b32 m0, s26
	s_nop 0
	global_load_lds_dwordx4 v176, s[4:5]
	s_waitcnt vmcnt(8)
	s_waitcnt lgkmcnt(0)
	s_barrier
	s_setprio 1
	v_mfma_f32_16x16x32_bf16 v[96:99], v[36:39], v[164:167], 0
	v_mfma_f32_16x16x32_bf16 v[92:95], v[44:47], v[164:167], 0
	v_mfma_f32_16x16x32_bf16 v[88:91], v[36:39], v[184:187], 0
	v_mfma_f32_16x16x32_bf16 v[84:87], v[44:47], v[184:187], 0
	v_mfma_f32_16x16x32_bf16 v[80:83], v[36:39], v[198:201], 0
	v_mfma_f32_16x16x32_bf16 v[76:79], v[44:47], v[198:201], 0
	v_mfma_f32_16x16x32_bf16 v[36:39], v[36:39], v[206:209], 0
	v_mfma_f32_16x16x32_bf16 v[96:99], v[40:43], v[168:171], v[96:99]
	v_mfma_f32_16x16x32_bf16 v[92:95], v[48:51], v[168:171], v[92:95]
	v_mfma_f32_16x16x32_bf16 v[88:91], v[40:43], v[188:191], v[88:91]
	v_mfma_f32_16x16x32_bf16 v[84:87], v[48:51], v[188:191], v[84:87]
	v_mfma_f32_16x16x32_bf16 v[80:83], v[40:43], v[202:205], v[80:83]
	v_mfma_f32_16x16x32_bf16 v[76:79], v[48:51], v[202:205], v[76:79]
	v_mfma_f32_16x16x32_bf16 v[36:39], v[40:43], v[210:213], v[36:39]
	v_mfma_f32_16x16x32_bf16 v[40:43], v[44:47], v[206:209], 0
	v_mfma_f32_16x16x32_bf16 v[40:43], v[48:51], v[210:213], v[40:43]
	s_setprio 0
	s_setprio 1
	v_mfma_f32_16x16x32_bf16 v[28:31], v[52:55], v[164:167], 0
	v_mfma_f32_16x16x32_bf16 v[32:35], v[60:63], v[164:167], 0
	v_mfma_f32_16x16x32_bf16 v[20:23], v[52:55], v[184:187], 0
	v_mfma_f32_16x16x32_bf16 v[24:27], v[60:63], v[184:187], 0
	v_mfma_f32_16x16x32_bf16 v[16:19], v[52:55], v[198:201], 0
	v_mfma_f32_16x16x32_bf16 v[12:15], v[60:63], v[198:201], 0
	v_mfma_f32_16x16x32_bf16 v[8:11], v[52:55], v[206:209], 0
	v_mfma_f32_16x16x32_bf16 v[4:7], v[60:63], v[206:209], 0
	v_mfma_f32_16x16x32_bf16 v[28:31], v[56:59], v[168:171], v[28:31]
	v_mfma_f32_16x16x32_bf16 v[32:35], v[64:67], v[168:171], v[32:35]
	v_mfma_f32_16x16x32_bf16 v[20:23], v[56:59], v[188:191], v[20:23]
	v_mfma_f32_16x16x32_bf16 v[24:27], v[64:67], v[188:191], v[24:27]
	v_mfma_f32_16x16x32_bf16 v[16:19], v[56:59], v[202:205], v[16:19]
	v_mfma_f32_16x16x32_bf16 v[12:15], v[64:67], v[202:205], v[12:15]
	v_mfma_f32_16x16x32_bf16 v[8:11], v[56:59], v[210:213], v[8:11]
	v_mfma_f32_16x16x32_bf16 v[4:7], v[64:67], v[210:213], v[4:7]
	s_setprio 0
	s_barrier
	s_branch .Lpe_join_108
	.p2align	6

; template <class Epi, class Sched, bool ALIGN_EPI = false, bool SP2 = false, bool ACHUNK = false>
; __device__ __forceinline__ void gemm_phase(PG8_LAS unsigned char* lds, const Gemm g, const Sched& S, const Epi& E) {
;     ...
;         const bool has_next = S.next(ui + 1, nxt);
;         const char* nA = has_next ? (const char*)g.A + (size_t)nxt.pm * tstepA : cA; const char* nB = has_next ? (const char*)g.Bt + (size_t)nxt.pn * tstepB : cB;
;         for (int t = 0; t < nt; t += 2) {
;             const bool last = (t == nt - 2);
;             if constexpr (Epi::HAS_MID) { if (t == Epi::MID_T) E.mid(acc, cur, wr, wc, fr, fq, ShflDev{}); }
;             const char* a1 = cA + (size_t)(t + 1) * kstep;
;             const char* a2 = last ? nA : cA + (size_t)(t + 2) * kstep; const char* b2 = last ? nB : cB + (size_t)(t + 2) * kstep;
.LBB0_215:
	s_add_u32 s48, s20, 0x100
	s_addc_u32 s49, s21, 0
	s_add_u32 s20, s22, 0x80
	s_addc_u32 s21, s23, 0
	s_mov_b32 s22, 0
	v_add_u32_e32 v192, 0x10000, v147
	.p2align	6

; #define PG8_STAGE(bufoff, gbase, voff) do { _Pragma("unroll") for (int _i = 0; _i < 2; ++_i) \
;         __builtin_amdgcn_global_load_lds((const unsigned*)((const char*)(gbase) + (voff)[_i]), (PG8_LAS unsigned*)(lds + (bufoff) + ldsw + _i * 8192), 16, 0, 0); } while (0)
; #define PG8_LDA(dst, b, h) do { _Pragma("unroll") for (int m = 0; m < 4; ++m) _Pragma("unroll") for (int k = 0; k < 2; ++k) dst[m][k] = *(const PG8_LAS bf16x8*)(lds + PG8_SA(b, h) + aoff + m * 2048 + k * 1024); } while (0)
; #define PG8_LDB(dst, b, h) do { _Pragma("unroll") for (int n = 0; n < 2; ++n) _Pragma("unroll") for (int k = 0; k < 2; ++k) dst[n][k] = *(const PG8_LAS bf16x8*)(lds + PG8_SB(b, h) + boff + n * 2048 + k * 1024); } while (0)
; #define PG8_WAIT_V(n) asm volatile("s_waitcnt vmcnt(" #n ")" ::: "memory")
; #define PG8_WAIT_L(n) asm volatile("s_waitcnt lgkmcnt(" #n ")" ::: "memory")
; template <class Epi, class Sched, bool ALIGN_EPI = false, bool SP2 = false, bool ACHUNK = false>
; __device__ __forceinline__ void gemm_phase(PG8_LAS unsigned char* lds, const Gemm g, const Sched& S, const Epi& E) {
;     ...
;         const bool has_next = S.next(ui + 1, nxt);
;         const char* nA = has_next ? (const char*)g.A + (size_t)nxt.pm * tstepA : cA; const char* nB = has_next ? (const char*)g.Bt + (size_t)nxt.pn * tstepB : cB;
;         for (int t = 0; t < nt; t += 2) {
;             const bool last = (t == nt - 2);
;             if constexpr (Epi::HAS_MID) { if (t == Epi::MID_T) E.mid(acc, cur, wr, wc, fr, fq, ShflDev{}); }
;             const char* a1 = cA + (size_t)(t + 1) * kstep;
;             const char* a2 = last ? nA : cA + (size_t)(t + 2) * kstep; const char* b2 = last ? nB : cB + (size_t)(t + 2) * kstep;
;             const char* a3 = a2 + kstep; const char* b3 = b2 + kstep;
;             if (last && has_next) S.a_ready(nxt);
;             if constexpr (SP2) {
;             PG8_LDB(B0, 0, 0); PG8_LDB(B1, 0, 1); PG8_SCHED; PG8_LDA(At, 0, 0); PG8_STAGE(PG8_SA(1, 1), a1 + hstepA, voffA);
;             PG8_WAIT_V(8); PG8_WAIT_L(0); PG8_BAR; PG8_MMA(0, 0, At, B0); PG8_MMA(0, 1, At, B1); PG8_BAR; PG8_SCHED;
;             PG8_LDA(At, 0, 1); PG8_STAGE(PG8_SB(0, 0), b2, voffB); PG8_STAGE(PG8_SB(0, 1), b2 + hstepB, voffB); PG8_STAGE(PG8_SA(0, 0), a2, voffA);
;             PG8_WAIT_V(8); PG8_WAIT_L(0); PG8_BAR; PG8_MMA(1, 0, At, B0); PG8_MMA(1, 1, At, B1); PG8_BAR; PG8_SCHED;
.LBB0_351:
	s_andn2_b64 vcc, exec, s[4:5]
	s_cbranch_vccnz .LBB0_342
	s_add_u32 s40, s18, 0x100
	s_addc_u32 s41, s19, 0
	s_add_u32 s18, s20, 0x80
	s_addc_u32 s19, s21, 0
	s_mov_b32 s20, 0
	v_add_u32_e32 v222, 0x10000, v143
	s_add_i32 s42, s20, 2
	s_add_u32 s43, s18, 0x80
	s_addc_u32 s21, s19, 0
	s_add_i32 s46, 0, 0x10000
	s_cmp_eq_u32 s33, s20
	s_cselect_b32 s21, s13, s21
	s_cselect_b32 s20, s12, s43
	s_cselect_b32 s45, s17, s41
	s_cselect_b32 s44, s16, s40
	s_add_i32 s43, 0, 0x14000
	ds_read_b128 v[154:157], v222
	ds_read_b128 v[158:161], v222 offset:1024
	ds_read_b128 v[162:165], v222 offset:2048
	ds_read_b128 v[166:169], v222 offset:3072
	ds_read_b128 v[170:173], v222 offset:16384
	ds_read_b128 v[174:177], v222 offset:17408
	ds_read_b128 v[178:181], v222 offset:18432
	ds_read_b128 v[182:185], v222 offset:19456
	s_add_i32 m0, s25, 0xc000
	ds_read_b128 v[186:189], v152
	ds_read_b128 v[190:193], v152 offset:1024
	ds_read_b128 v[198:201], v152 offset:2048
	ds_read_b128 v[202:205], v152 offset:3072
	ds_read_b128 v[206:209], v152 offset:4096
	ds_read_b128 v[210:213], v152 offset:5120
	ds_read_b128 v[214:217], v152 offset:6144
	ds_read_b128 v[218:221], v152 offset:7168
	global_load_lds_dwordx4 v138, s[18:19]
	s_add_i32 m0, s25, 0xe000
	s_nop 0
	global_load_lds_dwordx4 v140, s[18:19]
	s_waitcnt vmcnt(8)
	s_waitcnt lgkmcnt(0)
	s_barrier
	s_setprio 1
	v_mfma_f32_16x16x32_bf16 v[124:127], v[154:157], v[186:189], 0
	v_mfma_f32_16x16x32_bf16 v[128:131], v[162:165], v[186:189], 0
	v_mfma_f32_16x16x32_bf16 v[112:115], v[154:157], v[198:201], 0
	v_mfma_f32_16x16x32_bf16 v[108:111], v[162:165], v[198:201], 0
	v_mfma_f32_16x16x32_bf16 v[96:99], v[154:157], v[206:209], 0
	v_mfma_f32_16x16x32_bf16 v[92:95], v[162:165], v[206:209], 0
	v_mfma_f32_16x16x32_bf16 v[80:83], v[154:157], v[214:217], 0
	v_mfma_f32_16x16x32_bf16 v[76:79], v[162:165], v[214:217], 0
	v_mfma_f32_16x16x32_bf16 v[124:127], v[158:161], v[190:193], v[124:127]
	v_mfma_f32_16x16x32_bf16 v[128:131], v[166:169], v[190:193], v[128:131]
	v_mfma_f32_16x16x32_bf16 v[112:115], v[158:161], v[202:205], v[112:115]
	v_mfma_f32_16x16x32_bf16 v[108:111], v[166:169], v[202:205], v[108:111]
	v_mfma_f32_16x16x32_bf16 v[96:99], v[158:161], v[210:213], v[96:99]
	v_mfma_f32_16x16x32_bf16 v[92:95], v[166:169], v[210:213], v[92:95]
	v_mfma_f32_16x16x32_bf16 v[80:83], v[158:161], v[218:221], v[80:83]
	v_mfma_f32_16x16x32_bf16 v[76:79], v[166:169], v[218:221], v[76:79]
	s_setprio 0
	s_setprio 1
	v_mfma_f32_16x16x32_bf16 v[120:123], v[170:173], v[186:189], 0
	v_mfma_f32_16x16x32_bf16 v[116:119], v[178:181], v[186:189], 0
	v_mfma_f32_16x16x32_bf16 v[104:107], v[170:173], v[198:201], 0
	v_mfma_f32_16x16x32_bf16 v[100:103], v[178:181], v[198:201], 0
	v_mfma_f32_16x16x32_bf16 v[88:91], v[170:173], v[206:209], 0
	v_mfma_f32_16x16x32_bf16 v[84:87], v[178:181], v[206:209], 0
	v_mfma_f32_16x16x32_bf16 v[72:75], v[170:173], v[214:217], 0
	v_mfma_f32_16x16x32_bf16 v[68:71], v[178:181], v[214:217], 0
	v_mfma_f32_16x16x32_bf16 v[120:123], v[174:177], v[190:193], v[120:123]
	v_mfma_f32_16x16x32_bf16 v[116:119], v[182:185], v[190:193], v[116:119]
	v_mfma_f32_16x16x32_bf16 v[104:107], v[174:177], v[202:205], v[104:107]
	v_mfma_f32_16x16x32_bf16 v[100:103], v[182:185], v[202:205], v[100:103]
	v_mfma_f32_16x16x32_bf16 v[88:91], v[174:177], v[210:213], v[88:91]
	v_mfma_f32_16x16x32_bf16 v[84:87], v[182:185], v[210:213], v[84:87]
	v_mfma_f32_16x16x32_bf16 v[72:75], v[174:177], v[218:221], v[72:75]
	v_mfma_f32_16x16x32_bf16 v[68:71], v[182:185], v[218:221], v[68:71]
	s_setprio 0
	s_barrier
	s_add_i32 s46, s46, s24
	s_mov_b32 m0, s46
	ds_read_b128 v[186:189], v152 offset:16384
	ds_read_b128 v[190:193], v152 offset:17408
	ds_read_b128 v[198:201], v152 offset:18432
	ds_read_b128 v[202:205], v152 offset:19456
	ds_read_b128 v[206:209], v152 offset:20480
	ds_read_b128 v[210:213], v152 offset:21504
	ds_read_b128 v[214:217], v152 offset:22528
	ds_read_b128 v[218:221], v152 offset:23552
	global_load_lds_dwordx4 v2, s[44:45]
	s_add_i32 m0, s46, 0x2000
	s_add_i32 s43, s43, s24
	global_load_lds_dwordx4 v136, s[44:45]
	s_add_u32 s44, s44, s0
	s_addc_u32 s45, s45, s1
	s_mov_b64 vcc, s[44:45]
	s_sub_u32 s98, s44, s0
	s_subb_u32 s99, s45, s1
	s_mov_b32 m0, s43
	s_nop 0
	global_load_lds_dwordx4 v2, s[44:45]
	s_add_i32 m0, s43, 0x2000
	s_nop 0
	global_load_lds_dwordx4 v136, s[44:45]
	s_mov_b32 m0, s25
	s_nop 0
	global_load_lds_dwordx4 v132, s[20:21]
	s_mov_b32 m0, s26
	s_nop 0
	global_load_lds_dwordx4 v134, s[20:21]
	s_waitcnt vmcnt(8)
	s_waitcnt lgkmcnt(0)
	s_barrier
	s_setprio 1
	v_mfma_f32_16x16x32_bf16 v[64:67], v[154:157], v[186:189], 0
	v_mfma_f32_16x16x32_bf16 v[60:63], v[162:165], v[186:189], 0
	v_mfma_f32_16x16x32_bf16 v[48:51], v[154:157], v[198:201], 0
	v_mfma_f32_16x16x32_bf16 v[44:47], v[162:165], v[198:201], 0
	v_mfma_f32_16x16x32_bf16 v[32:35], v[154:157], v[206:209], 0
	v_mfma_f32_16x16x32_bf16 v[28:31], v[162:165], v[206:209], 0
	v_mfma_f32_16x16x32_bf16 v[16:19], v[154:157], v[214:217], 0
	v_mfma_f32_16x16x32_bf16 v[12:15], v[162:165], v[214:217], 0
	v_mfma_f32_16x16x32_bf16 v[64:67], v[158:161], v[190:193], v[64:67]
	v_mfma_f32_16x16x32_bf16 v[60:63], v[166:169], v[190:193], v[60:63]
	v_mfma_f32_16x16x32_bf16 v[48:51], v[158:161], v[202:205], v[48:51]
	v_mfma_f32_16x16x32_bf16 v[44:47], v[166:169], v[202:205], v[44:47]
	v_mfma_f32_16x16x32_bf16 v[32:35], v[158:161], v[210:213], v[32:35]
	v_mfma_f32_16x16x32_bf16 v[28:31], v[166:169], v[210:213], v[28:31]
	v_mfma_f32_16x16x32_bf16 v[16:19], v[158:161], v[218:221], v[16:19]
	v_mfma_f32_16x16x32_bf16 v[12:15], v[166:169], v[218:221], v[12:15]
	s_setprio 0
	s_setprio 1
	v_mfma_f32_16x16x32_bf16 v[56:59], v[170:173], v[186:189], 0
	v_mfma_f32_16x16x32_bf16 v[52:55], v[178:181], v[186:189], 0
	v_mfma_f32_16x16x32_bf16 v[40:43], v[170:173], v[198:201], 0
	v_mfma_f32_16x16x32_bf16 v[36:39], v[178:181], v[198:201], 0
	v_mfma_f32_16x16x32_bf16 v[24:27], v[170:173], v[206:209], 0
	v_mfma_f32_16x16x32_bf16 v[20:23], v[178:181], v[206:209], 0
	v_mfma_f32_16x16x32_bf16 v[8:11], v[170:173], v[214:217], 0
	v_mfma_f32_16x16x32_bf16 v[4:7], v[178:181], v[214:217], 0
	v_mfma_f32_16x16x32_bf16 v[56:59], v[174:177], v[190:193], v[56:59]
	v_mfma_f32_16x16x32_bf16 v[52:55], v[182:185], v[190:193], v[52:55]
	v_mfma_f32_16x16x32_bf16 v[40:43], v[174:177], v[202:205], v[40:43]
	v_mfma_f32_16x16x32_bf16 v[36:39], v[182:185], v[202:205], v[36:39]
	v_mfma_f32_16x16x32_bf16 v[24:27], v[174:177], v[210:213], v[24:27]
	v_mfma_f32_16x16x32_bf16 v[20:23], v[182:185], v[210:213], v[20:23]
	v_mfma_f32_16x16x32_bf16 v[8:11], v[174:177], v[218:221], v[8:11]
	v_mfma_f32_16x16x32_bf16 v[4:7], v[182:185], v[218:221], v[4:7]
	s_setprio 0
	s_barrier
	s_branch .Lpe_join_353
	.p2align	6

; #define PG8_STAGE(bufoff, gbase, voff) do { _Pragma("unroll") for (int _i = 0; _i < 2; ++_i) \
;         __builtin_amdgcn_global_load_lds((const unsigned*)((const char*)(gbase) + (voff)[_i]), (PG8_LAS unsigned*)(lds + (bufoff) + ldsw + _i * 8192), 16, 0, 0); } while (0)
; #define PG8_LDA(dst, b, h) do { _Pragma("unroll") for (int m = 0; m < 4; ++m) _Pragma("unroll") for (int k = 0; k < 2; ++k) dst[m][k] = *(const PG8_LAS bf16x8*)(lds + PG8_SA(b, h) + aoff + m * 2048 + k * 1024); } while (0)
; #define PG8_LDB(dst, b, h) do { _Pragma("unroll") for (int n = 0; n < 2; ++n) _Pragma("unroll") for (int k = 0; k < 2; ++k) dst[n][k] = *(const PG8_LAS bf16x8*)(lds + PG8_SB(b, h) + boff + n * 2048 + k * 1024); } while (0)
; #define PG8_WAIT_V(n) asm volatile("s_waitcnt vmcnt(" #n ")" ::: "memory")
; #define PG8_WAIT_L(n) asm volatile("s_waitcnt lgkmcnt(" #n ")" ::: "memory")
; template <class Epi, class Sched, bool ALIGN_EPI = false, bool SP2 = false, bool ACHUNK = false>
; __device__ __forceinline__ void gemm_phase(PG8_LAS unsigned char* lds, const Gemm g, const Sched& S, const Epi& E) {
;     ...
;         const bool has_next = S.next(ui + 1, nxt);
;         const char* nA = has_next ? (const char*)g.A + (size_t)nxt.pm * tstepA : cA; const char* nB = has_next ? (const char*)g.Bt + (size_t)nxt.pn * tstepB : cB;
;         for (int t = 0; t < nt; t += 2) {
;             const bool last = (t == nt - 2);
;             if constexpr (Epi::HAS_MID) { if (t == Epi::MID_T) E.mid(acc, cur, wr, wc, fr, fq, ShflDev{}); }
;             const char* a1 = cA + (size_t)(t + 1) * kstep;
;             const char* a2 = last ? nA : cA + (size_t)(t + 2) * kstep; const char* b2 = last ? nB : cB + (size_t)(t + 2) * kstep;
;             const char* a3 = a2 + kstep; const char* b3 = b2 + kstep;
;             if (last && has_next) S.a_ready(nxt);
;             if constexpr (SP2) {
;             PG8_LDB(B0, 0, 0); PG8_LDB(B1, 0, 1); PG8_SCHED; PG8_LDA(At, 0, 0); PG8_STAGE(PG8_SA(1, 1), a1 + hstepA, voffA);
;             PG8_WAIT_V(8); PG8_WAIT_L(0); PG8_BAR; PG8_MMA(0, 0, At, B0); PG8_MMA(0, 1, At, B1); PG8_BAR; PG8_SCHED;
;             PG8_LDA(At, 0, 1); PG8_STAGE(PG8_SB(0, 0), b2, voffB); PG8_STAGE(PG8_SB(0, 1), b2 + hstepB, voffB); PG8_STAGE(PG8_SA(0, 0), a2, voffA);
;             PG8_WAIT_V(8); PG8_WAIT_L(0); PG8_BAR; PG8_MMA(1, 0, At, B0); PG8_MMA(1, 1, At, B1); PG8_BAR; PG8_SCHED;
.LBB0_375:
	s_andn2_b64 vcc, exec, s[34:35]
	s_cbranch_vccnz .LBB0_379
	s_add_u32 s4, s4, 0x80
	s_addc_u32 s5, s5, 0
	s_add_u32 s8, s6, 0x100
	s_addc_u32 s9, s7, 0
	s_mov_b32 s6, 0
	v_add_u32_e32 v192, 0x10000, v175
	s_add_i32 s48, s6, 2
	s_add_u32 s49, s4, 0x80
	s_addc_u32 s7, s5, 0
	s_add_i32 s52, 0, 0x10000
	s_cmp_eq_u32 s27, s6
	s_cselect_b32 s7, s1, s7
	s_cselect_b32 s6, s0, s49
	s_cselect_b32 s51, s43, s9
	s_cselect_b32 s50, s42, s8
	s_add_i32 s49, 0, 0x14000
	s_waitcnt lgkmcnt(0)
	ds_read_b128 v[146:149], v192
	ds_read_b128 v[150:153], v192 offset:1024
	ds_read_b128 v[154:157], v192 offset:2048
	ds_read_b128 v[158:161], v192 offset:3072
	ds_read_b128 v[162:165], v192 offset:16384
	ds_read_b128 v[166:169], v192 offset:17408
	ds_read_b128 v[170:173], v192 offset:18432
	ds_read_b128 v[180:183], v192 offset:19456
	s_add_i32 m0, s20, 0xc000
	ds_read_b128 v[184:187], v179
	ds_read_b128 v[188:191], v179 offset:1024
	ds_read_b128 v[198:201], v179 offset:2048
	ds_read_b128 v[202:205], v179 offset:3072
	ds_read_b128 v[206:209], v179 offset:4096
	ds_read_b128 v[210:213], v179 offset:5120
	ds_read_b128 v[214:217], v179 offset:6144
	ds_read_b128 v[218:221], v179 offset:7168
	global_load_lds_dwordx4 v142, s[4:5]
	s_add_i32 m0, s20, 0xe000
	s_nop 0
	global_load_lds_dwordx4 v144, s[4:5]
	s_waitcnt vmcnt(8)
	s_waitcnt lgkmcnt(0)
	s_barrier
	s_setprio 1
	v_mfma_f32_16x16x32_bf16 v[124:127], v[146:149], v[184:187], 0
	v_mfma_f32_16x16x32_bf16 v[116:119], v[154:157], v[184:187], 0
	v_mfma_f32_16x16x32_bf16 v[108:111], v[146:149], v[198:201], 0
	v_mfma_f32_16x16x32_bf16 v[100:103], v[154:157], v[198:201], 0
	v_mfma_f32_16x16x32_bf16 v[92:95], v[146:149], v[206:209], 0
	v_mfma_f32_16x16x32_bf16 v[84:87], v[154:157], v[206:209], 0
	v_mfma_f32_16x16x32_bf16 v[76:79], v[146:149], v[214:217], 0
	v_mfma_f32_16x16x32_bf16 v[68:71], v[154:157], v[214:217], 0
	v_mfma_f32_16x16x32_bf16 v[124:127], v[150:153], v[188:191], v[124:127]
	v_mfma_f32_16x16x32_bf16 v[116:119], v[158:161], v[188:191], v[116:119]
	v_mfma_f32_16x16x32_bf16 v[108:111], v[150:153], v[202:205], v[108:111]
	v_mfma_f32_16x16x32_bf16 v[100:103], v[158:161], v[202:205], v[100:103]
	v_mfma_f32_16x16x32_bf16 v[92:95], v[150:153], v[210:213], v[92:95]
	v_mfma_f32_16x16x32_bf16 v[84:87], v[158:161], v[210:213], v[84:87]
	v_mfma_f32_16x16x32_bf16 v[76:79], v[150:153], v[218:221], v[76:79]
	v_mfma_f32_16x16x32_bf16 v[68:71], v[158:161], v[218:221], v[68:71]
	s_setprio 0
	s_setprio 1
	v_mfma_f32_16x16x32_bf16 v[128:131], v[162:165], v[184:187], 0
	v_mfma_f32_16x16x32_bf16 v[120:123], v[170:173], v[184:187], 0
	v_mfma_f32_16x16x32_bf16 v[112:115], v[162:165], v[198:201], 0
	v_mfma_f32_16x16x32_bf16 v[104:107], v[170:173], v[198:201], 0
	v_mfma_f32_16x16x32_bf16 v[96:99], v[162:165], v[206:209], 0
	v_mfma_f32_16x16x32_bf16 v[88:91], v[170:173], v[206:209], 0
	v_mfma_f32_16x16x32_bf16 v[80:83], v[162:165], v[214:217], 0
	v_mfma_f32_16x16x32_bf16 v[72:75], v[170:173], v[214:217], 0
	v_mfma_f32_16x16x32_bf16 v[128:131], v[166:169], v[188:191], v[128:131]
	v_mfma_f32_16x16x32_bf16 v[120:123], v[180:183], v[188:191], v[120:123]
	v_mfma_f32_16x16x32_bf16 v[112:115], v[166:169], v[202:205], v[112:115]
	v_mfma_f32_16x16x32_bf16 v[104:107], v[180:183], v[202:205], v[104:107]
	v_mfma_f32_16x16x32_bf16 v[96:99], v[166:169], v[210:213], v[96:99]
	v_mfma_f32_16x16x32_bf16 v[88:91], v[180:183], v[210:213], v[88:91]
	v_mfma_f32_16x16x32_bf16 v[80:83], v[166:169], v[218:221], v[80:83]
	v_mfma_f32_16x16x32_bf16 v[72:75], v[180:183], v[218:221], v[72:75]
	s_setprio 0
	s_barrier
	s_add_i32 s52, s52, s13
	s_mov_b32 m0, s52
	ds_read_b128 v[184:187], v179 offset:16384
	ds_read_b128 v[188:191], v179 offset:17408
	ds_read_b128 v[198:201], v179 offset:18432
	ds_read_b128 v[202:205], v179 offset:19456
	ds_read_b128 v[206:209], v179 offset:20480
	ds_read_b128 v[210:213], v179 offset:21504
	ds_read_b128 v[214:217], v179 offset:22528
	ds_read_b128 v[218:221], v179 offset:23552
	global_load_lds_dwordx4 v134, s[50:51]
	s_add_i32 m0, s52, 0x2000
	s_add_i32 s49, s49, s13
	global_load_lds_dwordx4 v138, s[50:51]
	s_add_u32 s50, s50, s18
	s_addc_u32 s51, s51, s19
	s_mov_b64 vcc, s[50:51]
	s_sub_u32 s98, s50, s18
	s_subb_u32 s99, s51, s19
	s_mov_b32 m0, s49
	s_nop 0
	global_load_lds_dwordx4 v134, s[50:51]
	s_add_i32 m0, s49, 0x2000
	s_nop 0
	global_load_lds_dwordx4 v138, s[50:51]
	s_mov_b32 m0, s20
	s_nop 0
	global_load_lds_dwordx4 v132, s[6:7]
	s_mov_b32 m0, s21
	s_nop 0
	global_load_lds_dwordx4 v136, s[6:7]
	s_waitcnt vmcnt(8)
	s_waitcnt lgkmcnt(0)
	s_barrier
	s_setprio 1
	v_mfma_f32_16x16x32_bf16 v[60:63], v[146:149], v[184:187], 0
	v_mfma_f32_16x16x32_bf16 v[52:55], v[154:157], v[184:187], 0
	v_mfma_f32_16x16x32_bf16 v[44:47], v[146:149], v[198:201], 0
	v_mfma_f32_16x16x32_bf16 v[36:39], v[154:157], v[198:201], 0
	v_mfma_f32_16x16x32_bf16 v[28:31], v[146:149], v[206:209], 0
	v_mfma_f32_16x16x32_bf16 v[20:23], v[154:157], v[206:209], 0
	v_mfma_f32_16x16x32_bf16 v[12:15], v[146:149], v[214:217], 0
	v_mfma_f32_16x16x32_bf16 v[4:7], v[154:157], v[214:217], 0
	v_mfma_f32_16x16x32_bf16 v[60:63], v[150:153], v[188:191], v[60:63]
	v_mfma_f32_16x16x32_bf16 v[52:55], v[158:161], v[188:191], v[52:55]
	v_mfma_f32_16x16x32_bf16 v[44:47], v[150:153], v[202:205], v[44:47]
	v_mfma_f32_16x16x32_bf16 v[36:39], v[158:161], v[202:205], v[36:39]
	v_mfma_f32_16x16x32_bf16 v[28:31], v[150:153], v[210:213], v[28:31]
	v_mfma_f32_16x16x32_bf16 v[20:23], v[158:161], v[210:213], v[20:23]
	v_mfma_f32_16x16x32_bf16 v[12:15], v[150:153], v[218:221], v[12:15]
	v_mfma_f32_16x16x32_bf16 v[4:7], v[158:161], v[218:221], v[4:7]
	s_setprio 0
	s_setprio 1
	v_mfma_f32_16x16x32_bf16 v[64:67], v[162:165], v[184:187], 0
	v_mfma_f32_16x16x32_bf16 v[56:59], v[170:173], v[184:187], 0
	v_mfma_f32_16x16x32_bf16 v[48:51], v[162:165], v[198:201], 0
	v_mfma_f32_16x16x32_bf16 v[40:43], v[170:173], v[198:201], 0
	v_mfma_f32_16x16x32_bf16 v[32:35], v[162:165], v[206:209], 0
	v_mfma_f32_16x16x32_bf16 v[24:27], v[170:173], v[206:209], 0
	v_mfma_f32_16x16x32_bf16 v[16:19], v[162:165], v[214:217], 0
	v_mfma_f32_16x16x32_bf16 v[8:11], v[170:173], v[214:217], 0
	v_mfma_f32_16x16x32_bf16 v[64:67], v[166:169], v[188:191], v[64:67]
	v_mfma_f32_16x16x32_bf16 v[56:59], v[180:183], v[188:191], v[56:59]
	v_mfma_f32_16x16x32_bf16 v[48:51], v[166:169], v[202:205], v[48:51]
	v_mfma_f32_16x16x32_bf16 v[40:43], v[180:183], v[202:205], v[40:43]
	v_mfma_f32_16x16x32_bf16 v[32:35], v[166:169], v[210:213], v[32:35]
	v_mfma_f32_16x16x32_bf16 v[24:27], v[180:183], v[210:213], v[24:27]
	v_mfma_f32_16x16x32_bf16 v[16:19], v[166:169], v[218:221], v[16:19]
	v_mfma_f32_16x16x32_bf16 v[8:11], v[180:183], v[218:221], v[8:11]
	s_setprio 0
	s_barrier
	s_branch .Lpe_join_377
	.p2align	6

; #define PG8_STAGE(bufoff, gbase, voff) do { _Pragma("unroll") for (int _i = 0; _i < 2; ++_i) \
;         __builtin_amdgcn_global_load_lds((const unsigned*)((const char*)(gbase) + (voff)[_i]), (PG8_LAS unsigned*)(lds + (bufoff) + ldsw + _i * 8192), 16, 0, 0); } while (0)
; #define PG8_LDA(dst, b, h) do { _Pragma("unroll") for (int m = 0; m < 4; ++m) _Pragma("unroll") for (int k = 0; k < 2; ++k) dst[m][k] = *(const PG8_LAS bf16x8*)(lds + PG8_SA(b, h) + aoff + m * 2048 + k * 1024); } while (0)
; #define PG8_LDB(dst, b, h) do { _Pragma("unroll") for (int n = 0; n < 2; ++n) _Pragma("unroll") for (int k = 0; k < 2; ++k) dst[n][k] = *(const PG8_LAS bf16x8*)(lds + PG8_SB(b, h) + boff + n * 2048 + k * 1024); } while (0)
; #define PG8_WAIT_V(n) asm volatile("s_waitcnt vmcnt(" #n ")" ::: "memory")
; #define PG8_WAIT_L(n) asm volatile("s_waitcnt lgkmcnt(" #n ")" ::: "memory")
; template <class Epi, class Sched, bool ALIGN_EPI = false, bool SP2 = false, bool ACHUNK = false>
; __device__ __forceinline__ void gemm_phase(PG8_LAS unsigned char* lds, const Gemm g, const Sched& S, const Epi& E) {
;     ...
;         const bool has_next = S.next(ui + 1, nxt);
;         const char* nA = has_next ? (const char*)g.A + (size_t)nxt.pm * tstepA : cA; const char* nB = has_next ? (const char*)g.Bt + (size_t)nxt.pn * tstepB : cB;
;         for (int t = 0; t < nt; t += 2) {
;             const bool last = (t == nt - 2);
;             if constexpr (Epi::HAS_MID) { if (t == Epi::MID_T) E.mid(acc, cur, wr, wc, fr, fq, ShflDev{}); }
;             const char* a1 = cA + (size_t)(t + 1) * kstep;
;             const char* a2 = last ? nA : cA + (size_t)(t + 2) * kstep; const char* b2 = last ? nB : cB + (size_t)(t + 2) * kstep;
;             const char* a3 = a2 + kstep; const char* b3 = b2 + kstep;
;             if (last && has_next) S.a_ready(nxt);
;             if constexpr (SP2) {
;             PG8_LDB(B0, 0, 0); PG8_LDB(B1, 0, 1); PG8_SCHED; PG8_LDA(At, 0, 0); PG8_STAGE(PG8_SA(1, 1), a1 + hstepA, voffA);
;             PG8_WAIT_V(8); PG8_WAIT_L(0); PG8_BAR; PG8_MMA(0, 0, At, B0); PG8_MMA(0, 1, At, B1); PG8_BAR; PG8_SCHED;
;             PG8_LDA(At, 0, 1); PG8_STAGE(PG8_SB(0, 0), b2, voffB); PG8_STAGE(PG8_SB(0, 1), b2 + hstepB, voffB); PG8_STAGE(PG8_SA(0, 0), a2, voffA);
;             PG8_WAIT_V(8); PG8_WAIT_L(0); PG8_BAR; PG8_MMA(1, 0, At, B0); PG8_MMA(1, 1, At, B1); PG8_BAR; PG8_SCHED;
.Lnl_pl_pe:
	s_add_i32 s9, 0, 0x14000
	ds_read_b128 v[132:135], v214
	ds_read_b128 v[136:139], v214 offset:1024
	ds_read_b128 v[140:143], v214 offset:2048
	ds_read_b128 v[144:147], v214 offset:3072
	ds_read_b128 v[148:151], v214 offset:16384
	ds_read_b128 v[152:155], v214 offset:17408
	ds_read_b128 v[156:159], v214 offset:18432
	ds_read_b128 v[160:163], v214 offset:19456
	s_add_i32 m0, s27, 0xc000
	ds_read_b128 v[178:181], v223
	ds_read_b128 v[182:185], v223 offset:1024
	ds_read_b128 v[186:189], v223 offset:2048
	ds_read_b128 v[190:193], v223 offset:3072
	ds_read_b128 v[198:201], v223 offset:4096
	ds_read_b128 v[202:205], v223 offset:5120
	ds_read_b128 v[206:209], v223 offset:6144
	ds_read_b128 v[210:213], v223 offset:7168
	global_load_lds_dwordx4 v174, s[0:1]
	s_add_i32 m0, s27, 0xe000
	s_nop 0
	global_load_lds_dwordx4 v176, s[0:1]
	s_waitcnt vmcnt(8)
	s_waitcnt lgkmcnt(0)
	s_barrier
	s_setprio 1
	v_mfma_f32_16x16x32_bf16 v[128:131], v[132:135], v[178:181], 0
	v_mfma_f32_16x16x32_bf16 v[124:127], v[140:143], v[178:181], 0
	v_mfma_f32_16x16x32_bf16 v[112:115], v[132:135], v[186:189], 0
	v_mfma_f32_16x16x32_bf16 v[108:111], v[140:143], v[186:189], 0
	v_mfma_f32_16x16x32_bf16 v[96:99], v[132:135], v[198:201], 0
	v_mfma_f32_16x16x32_bf16 v[92:95], v[140:143], v[198:201], 0
	v_mfma_f32_16x16x32_bf16 v[80:83], v[132:135], v[206:209], 0
	v_mfma_f32_16x16x32_bf16 v[76:79], v[140:143], v[206:209], 0
	v_mfma_f32_16x16x32_bf16 v[128:131], v[136:139], v[182:185], v[128:131]
	v_mfma_f32_16x16x32_bf16 v[124:127], v[144:147], v[182:185], v[124:127]
	v_mfma_f32_16x16x32_bf16 v[112:115], v[136:139], v[190:193], v[112:115]
	v_mfma_f32_16x16x32_bf16 v[108:111], v[144:147], v[190:193], v[108:111]
	v_mfma_f32_16x16x32_bf16 v[96:99], v[136:139], v[202:205], v[96:99]
	v_mfma_f32_16x16x32_bf16 v[92:95], v[144:147], v[202:205], v[92:95]
	v_mfma_f32_16x16x32_bf16 v[80:83], v[136:139], v[210:213], v[80:83]
	v_mfma_f32_16x16x32_bf16 v[76:79], v[144:147], v[210:213], v[76:79]
	s_setprio 0
	s_setprio 1
	v_mfma_f32_16x16x32_bf16 v[120:123], v[148:151], v[178:181], 0
	v_mfma_f32_16x16x32_bf16 v[116:119], v[156:159], v[178:181], 0
	v_mfma_f32_16x16x32_bf16 v[104:107], v[148:151], v[186:189], 0
	v_mfma_f32_16x16x32_bf16 v[100:103], v[156:159], v[186:189], 0
	v_mfma_f32_16x16x32_bf16 v[88:91], v[148:151], v[198:201], 0
	v_mfma_f32_16x16x32_bf16 v[84:87], v[156:159], v[198:201], 0
	v_mfma_f32_16x16x32_bf16 v[72:75], v[148:151], v[206:209], 0
	v_mfma_f32_16x16x32_bf16 v[68:71], v[156:159], v[206:209], 0
	v_mfma_f32_16x16x32_bf16 v[120:123], v[152:155], v[182:185], v[120:123]
	v_mfma_f32_16x16x32_bf16 v[116:119], v[160:163], v[182:185], v[116:119]
	v_mfma_f32_16x16x32_bf16 v[104:107], v[152:155], v[190:193], v[104:107]
	v_mfma_f32_16x16x32_bf16 v[100:103], v[160:163], v[190:193], v[100:103]
	v_mfma_f32_16x16x32_bf16 v[88:91], v[152:155], v[202:205], v[88:91]
	v_mfma_f32_16x16x32_bf16 v[84:87], v[160:163], v[202:205], v[84:87]
	v_mfma_f32_16x16x32_bf16 v[72:75], v[152:155], v[210:213], v[72:75]
	v_mfma_f32_16x16x32_bf16 v[68:71], v[160:163], v[210:213], v[68:71]
	s_setprio 0
	s_barrier
	s_add_i32 s15, s15, s26
	s_mov_b32 m0, s15
	ds_read_b128 v[178:181], v223 offset:16384
	ds_read_b128 v[182:185], v223 offset:17408
	ds_read_b128 v[186:189], v223 offset:18432
	ds_read_b128 v[190:193], v223 offset:19456
	ds_read_b128 v[198:201], v223 offset:20480
	ds_read_b128 v[202:205], v223 offset:21504
	ds_read_b128 v[206:209], v223 offset:22528
	ds_read_b128 v[210:213], v223 offset:23552
	global_load_lds_dwordx4 v2, s[16:17]
	s_add_i32 m0, s15, 0x2000
	s_add_i32 s9, s9, s26
	global_load_lds_dwordx4 v168, s[16:17]
	s_add_u32 s16, s16, s18
	s_addc_u32 s17, s17, s19
	s_mov_b64 vcc, s[16:17]
	s_sub_u32 s98, s16, s18
	s_subb_u32 s99, s17, s19
	s_mov_b32 m0, s9
	s_nop 0
	global_load_lds_dwordx4 v2, s[16:17]
	s_add_i32 m0, s9, 0x2000
	s_nop 0
	global_load_lds_dwordx4 v168, s[16:17]
	s_mov_b32 m0, s27
	s_nop 0
	global_load_lds_dwordx4 v164, s[4:5]
	s_mov_b32 m0, s36
	s_nop 0
	global_load_lds_dwordx4 v166, s[4:5]
	s_waitcnt vmcnt(8)
	s_waitcnt lgkmcnt(0)
	s_barrier
	s_setprio 1
	v_mfma_f32_16x16x32_bf16 v[64:67], v[132:135], v[178:181], 0
	v_mfma_f32_16x16x32_bf16 v[60:63], v[140:143], v[178:181], 0
	v_mfma_f32_16x16x32_bf16 v[48:51], v[132:135], v[186:189], 0
	v_mfma_f32_16x16x32_bf16 v[44:47], v[140:143], v[186:189], 0
	v_mfma_f32_16x16x32_bf16 v[32:35], v[132:135], v[198:201], 0
	v_mfma_f32_16x16x32_bf16 v[28:31], v[140:143], v[198:201], 0
	v_mfma_f32_16x16x32_bf16 v[16:19], v[132:135], v[206:209], 0
	v_mfma_f32_16x16x32_bf16 v[12:15], v[140:143], v[206:209], 0
	v_mfma_f32_16x16x32_bf16 v[64:67], v[136:139], v[182:185], v[64:67]
	v_mfma_f32_16x16x32_bf16 v[60:63], v[144:147], v[182:185], v[60:63]
	v_mfma_f32_16x16x32_bf16 v[48:51], v[136:139], v[190:193], v[48:51]
	v_mfma_f32_16x16x32_bf16 v[44:47], v[144:147], v[190:193], v[44:47]
	v_mfma_f32_16x16x32_bf16 v[32:35], v[136:139], v[202:205], v[32:35]
	v_mfma_f32_16x16x32_bf16 v[28:31], v[144:147], v[202:205], v[28:31]
	v_mfma_f32_16x16x32_bf16 v[16:19], v[136:139], v[210:213], v[16:19]
	v_mfma_f32_16x16x32_bf16 v[12:15], v[144:147], v[210:213], v[12:15]
	s_setprio 0
	s_setprio 1
	v_mfma_f32_16x16x32_bf16 v[56:59], v[148:151], v[178:181], 0
	v_mfma_f32_16x16x32_bf16 v[52:55], v[156:159], v[178:181], 0
	v_mfma_f32_16x16x32_bf16 v[40:43], v[148:151], v[186:189], 0
	v_mfma_f32_16x16x32_bf16 v[36:39], v[156:159], v[186:189], 0
	v_mfma_f32_16x16x32_bf16 v[24:27], v[148:151], v[198:201], 0
	v_mfma_f32_16x16x32_bf16 v[20:23], v[156:159], v[198:201], 0
	v_mfma_f32_16x16x32_bf16 v[8:11], v[148:151], v[206:209], 0
	v_mfma_f32_16x16x32_bf16 v[4:7], v[156:159], v[206:209], 0
	v_mfma_f32_16x16x32_bf16 v[56:59], v[152:155], v[182:185], v[56:59]
	v_mfma_f32_16x16x32_bf16 v[52:55], v[160:163], v[182:185], v[52:55]
	v_mfma_f32_16x16x32_bf16 v[40:43], v[152:155], v[190:193], v[40:43]
	v_mfma_f32_16x16x32_bf16 v[36:39], v[160:163], v[190:193], v[36:39]
	v_mfma_f32_16x16x32_bf16 v[24:27], v[152:155], v[202:205], v[24:27]
	v_mfma_f32_16x16x32_bf16 v[20:23], v[160:163], v[202:205], v[20:23]
	v_mfma_f32_16x16x32_bf16 v[8:11], v[152:155], v[210:213], v[8:11]
	v_mfma_f32_16x16x32_bf16 v[4:7], v[160:163], v[210:213], v[4:7]
	s_setprio 0
	s_barrier
	s_branch .Lpe_join_431
	.p2align	6
